# plus: top-k list compaction passes also stop at the last admissible row tile
# speedup vs baseline: 1.0354x; 1.0028x over previous
; __device__ __forceinline__ void topk_list(const unsigned (&uk)[32], LAS int* list, LAS float* listr, LAS unsigned* listT, const GAS f32x4* sak, int lane) {
;     ...
;     int base = 0, eqseen = 0;
; #pragma unroll
;     for (int rr = 0; rr < 32; ++rr) {
;         const bool gt = uk[rr] > T, eq = uk[rr] == T;
;         const unsigned long long meq = __builtin_amdgcn_ballot_w64(eq);
;         const int erank = eqseen + (int)__builtin_amdgcn_mbcnt_hi((unsigned)(meq >> 32), __builtin_amdgcn_mbcnt_lo((unsigned)meq, 0u));
;         const bool sel = gt || (eq && erank < need_eq);
;         const unsigned long long ms = __builtin_amdgcn_ballot_w64(sel);
;         const int pos = base + (int)__builtin_amdgcn_mbcnt_hi((unsigned)(ms >> 32), __builtin_amdgcn_mbcnt_lo((unsigned)ms, 0u));
;         if (sel) { list[pos] = 64 * rr + lane; listT[((pos >> 5) * 4 + (pos & 3)) * 8 + ((pos >> 2) & 7)] = (unsigned)(64 * rr + lane) * 512u; }
;         base += __builtin_popcountll(ms); eqseen += __builtin_popcountll(meq);
;     }
.LBB0_780:
	s_or_b64 exec, exec, s[50:51]
	s_cmpk_le_u32 s81, 0x200
	s_cbranch_scc1 .LBB0_876
	s_bcnt1_i32_b64 s50, s[52:53]
	s_add_i32 s58, s60, s50
	v_cmp_eq_u32_e64 s[50:51], v145, v85
	s_mov_b64 s[56:57], -1
	s_and_saveexec_b64 s[52:53], s[48:49]
	v_mbcnt_lo_u32_b32 v6, s50, 0
	v_mbcnt_hi_u32_b32 v6, s51, v6
	v_add_u32_e32 v6, s58, v6
	v_cmp_gt_i32_e64 s[48:49], s82, v6
	s_and_b64 s[48:49], s[50:51], s[48:49]
	s_orn2_b64 s[56:57], s[48:49], exec
	s_or_b64 exec, exec, s[52:53]
	s_bcnt1_i32_b64 s48, s[54:55]
	v_cndmask_b32_e64 v6, 0, 1, s[56:57]
	s_waitcnt vmcnt(6)
	v_or_b32_e32 v22, 0x200, v124
	s_add_i32 s59, s61, s48
	v_cmp_ne_u32_e64 s[52:53], 0, v6
	v_lshlrev_b32_e32 v19, 9, v22
	s_and_saveexec_b64 s[48:49], s[56:57]
	s_cbranch_execz .LBB0_784
	v_mbcnt_lo_u32_b32 v6, s52, 0
	v_mbcnt_hi_u32_b32 v6, s53, v6
	v_add_u32_e32 v6, s59, v6
	v_lshl_add_u32 v7, v6, 2, s33
	ds_write_b32 v7, v22
	v_and_b32_e32 v7, 0x7fe0, v6
	v_lshlrev_b32_e32 v20, 5, v6
	v_lshl_add_u32 v7, v7, 2, s33
	v_and_b32_e32 v20, 0x60, v20
	v_and_b32_e32 v6, 28, v6
	v_add3_u32 v6, v7, v20, v6
	ds_write_b32 v6, v19 offset:4096

; __device__ __forceinline__ void topk_list(const unsigned (&uk)[32], LAS int* list, LAS float* listr, LAS unsigned* listT, const GAS f32x4* sak, int lane) {
;     ...
;     int base = 0, eqseen = 0;
; #pragma unroll
;     for (int rr = 0; rr < 32; ++rr) {
;         const bool gt = uk[rr] > T, eq = uk[rr] == T;
;         const unsigned long long meq = __builtin_amdgcn_ballot_w64(eq);
;         const int erank = eqseen + (int)__builtin_amdgcn_mbcnt_hi((unsigned)(meq >> 32), __builtin_amdgcn_mbcnt_lo((unsigned)meq, 0u));
;         const bool sel = gt || (eq && erank < need_eq);
;         const unsigned long long ms = __builtin_amdgcn_ballot_w64(sel);
;         const int pos = base + (int)__builtin_amdgcn_mbcnt_hi((unsigned)(ms >> 32), __builtin_amdgcn_mbcnt_lo((unsigned)ms, 0u));
;         if (sel) { list[pos] = 64 * rr + lane; listT[((pos >> 5) * 4 + (pos & 3)) * 8 + ((pos >> 2) & 7)] = (unsigned)(64 * rr + lane) * 512u; }
;         base += __builtin_popcountll(ms); eqseen += __builtin_popcountll(meq);
;     }
.LBB0_796:
	s_or_b64 exec, exec, s[42:43]
	s_cmpk_le_u32 s81, 0x300
	s_cbranch_scc1 .LBB0_876
	s_bcnt1_i32_b64 s42, s[44:45]
	s_add_i32 s50, s52, s42
	v_cmp_eq_u32_e64 s[42:43], v159, v85
	s_mov_b64 s[48:49], -1
	s_and_saveexec_b64 s[44:45], s[40:41]
	v_mbcnt_lo_u32_b32 v6, s42, 0
	v_mbcnt_hi_u32_b32 v6, s43, v6
	v_add_u32_e32 v6, s50, v6
	v_cmp_gt_i32_e64 s[40:41], s82, v6
	s_and_b64 s[40:41], s[42:43], s[40:41]
	s_orn2_b64 s[48:49], s[40:41], exec
	s_or_b64 exec, exec, s[44:45]
	s_bcnt1_i32_b64 s40, s[46:47]
	v_cndmask_b32_e64 v6, 0, 1, s[48:49]
	s_waitcnt vmcnt(4)
	v_or_b32_e32 v30, 0x300, v124
	s_add_i32 s51, s53, s40
	v_cmp_ne_u32_e64 s[44:45], 0, v6
	v_lshlrev_b32_e32 v25, 9, v30
	s_and_saveexec_b64 s[40:41], s[48:49]
	s_cbranch_execz .LBB0_800
	v_mbcnt_lo_u32_b32 v6, s44, 0
	v_mbcnt_hi_u32_b32 v6, s45, v6
	v_add_u32_e32 v6, s51, v6
	v_lshl_add_u32 v7, v6, 2, s33
	ds_write_b32 v7, v30
	v_and_b32_e32 v7, 0x7ffe0, v6
	v_lshlrev_b32_e32 v27, 5, v6
	v_lshl_add_u32 v7, v7, 2, s33
	v_and_b32_e32 v27, 0x60, v27
	v_and_b32_e32 v6, 28, v6
	v_add3_u32 v6, v7, v27, v6
	ds_write_b32 v6, v25 offset:4096

; __device__ __forceinline__ void topk_list(const unsigned (&uk)[32], LAS int* list, LAS float* listr, LAS unsigned* listT, const GAS f32x4* sak, int lane) {
;     ...
;     int base = 0, eqseen = 0;
; #pragma unroll
;     for (int rr = 0; rr < 32; ++rr) {
;         const bool gt = uk[rr] > T, eq = uk[rr] == T;
;         const unsigned long long meq = __builtin_amdgcn_ballot_w64(eq);
;         const int erank = eqseen + (int)__builtin_amdgcn_mbcnt_hi((unsigned)(meq >> 32), __builtin_amdgcn_mbcnt_lo((unsigned)meq, 0u));
;         const bool sel = gt || (eq && erank < need_eq);
;         const unsigned long long ms = __builtin_amdgcn_ballot_w64(sel);
;         const int pos = base + (int)__builtin_amdgcn_mbcnt_hi((unsigned)(ms >> 32), __builtin_amdgcn_mbcnt_lo((unsigned)ms, 0u));
;         if (sel) { list[pos] = 64 * rr + lane; listT[((pos >> 5) * 4 + (pos & 3)) * 8 + ((pos >> 2) & 7)] = (unsigned)(64 * rr + lane) * 512u; }
;         base += __builtin_popcountll(ms); eqseen += __builtin_popcountll(meq);
;     }
.LBB0_812:
	s_or_b64 exec, exec, s[34:35]
	s_cmpk_le_u32 s81, 0x400
	s_cbranch_scc1 .LBB0_876
	s_bcnt1_i32_b64 s34, s[36:37]
	s_add_i32 s42, s44, s34
	v_cmp_eq_u32_e64 s[34:35], v167, v85
	s_mov_b64 s[40:41], -1
	s_and_saveexec_b64 s[36:37], s[30:31]
	v_mbcnt_lo_u32_b32 v6, s34, 0
	v_mbcnt_hi_u32_b32 v6, s35, v6
	v_add_u32_e32 v6, s42, v6
	v_cmp_gt_i32_e64 s[30:31], s82, v6
	s_and_b64 s[30:31], s[34:35], s[30:31]
	s_orn2_b64 s[40:41], s[30:31], exec
	s_or_b64 exec, exec, s[36:37]
	s_bcnt1_i32_b64 s30, s[38:39]
	v_cndmask_b32_e64 v6, 0, 1, s[40:41]
	v_or_b32_e32 v43, 0x400, v124
	s_add_i32 s43, s45, s30
	v_cmp_ne_u32_e64 s[36:37], 0, v6
	v_lshlrev_b32_e32 v33, 9, v43
	s_and_saveexec_b64 s[30:31], s[40:41]
	s_cbranch_execz .LBB0_816
	v_mbcnt_lo_u32_b32 v6, s36, 0
	v_mbcnt_hi_u32_b32 v6, s37, v6
	v_add_u32_e32 v6, s43, v6
	v_lshl_add_u32 v7, v6, 2, s33
	ds_write_b32 v7, v43
	v_and_b32_e32 v7, 0x7fffe0, v6
	v_lshlrev_b32_e32 v40, 5, v6
	v_lshl_add_u32 v7, v7, 2, s33
	v_and_b32_e32 v40, 0x60, v40
	v_and_b32_e32 v6, 28, v6
	v_add3_u32 v6, v7, v40, v6
	ds_write_b32 v6, v33 offset:4096

; __device__ __forceinline__ void topk_list(const unsigned (&uk)[32], LAS int* list, LAS float* listr, LAS unsigned* listT, const GAS f32x4* sak, int lane) {
;     ...
;     int base = 0, eqseen = 0;
; #pragma unroll
;     for (int rr = 0; rr < 32; ++rr) {
;         const bool gt = uk[rr] > T, eq = uk[rr] == T;
;         const unsigned long long meq = __builtin_amdgcn_ballot_w64(eq);
;         const int erank = eqseen + (int)__builtin_amdgcn_mbcnt_hi((unsigned)(meq >> 32), __builtin_amdgcn_mbcnt_lo((unsigned)meq, 0u));
;         const bool sel = gt || (eq && erank < need_eq);
;         const unsigned long long ms = __builtin_amdgcn_ballot_w64(sel);
;         const int pos = base + (int)__builtin_amdgcn_mbcnt_hi((unsigned)(ms >> 32), __builtin_amdgcn_mbcnt_lo((unsigned)ms, 0u));
;         if (sel) { list[pos] = 64 * rr + lane; listT[((pos >> 5) * 4 + (pos & 3)) * 8 + ((pos >> 2) & 7)] = (unsigned)(64 * rr + lane) * 512u; }
;         base += __builtin_popcountll(ms); eqseen += __builtin_popcountll(meq);
;     }
.LBB0_828:
	s_or_b64 exec, exec, s[24:25]
	s_cmpk_le_u32 s81, 0x500
	s_cbranch_scc1 .LBB0_876
	s_bcnt1_i32_b64 s24, s[26:27]
	s_add_i32 s34, s36, s24
	v_cmp_eq_u32_e64 s[24:25], v171, v85
	s_mov_b64 s[30:31], -1
	s_and_saveexec_b64 s[26:27], s[22:23]
	v_mbcnt_lo_u32_b32 v6, s24, 0
	v_mbcnt_hi_u32_b32 v6, s25, v6
	v_add_u32_e32 v6, s34, v6
	v_cmp_gt_i32_e64 s[22:23], s82, v6
	s_and_b64 s[22:23], s[24:25], s[22:23]
	s_orn2_b64 s[30:31], s[22:23], exec
	s_or_b64 exec, exec, s[26:27]
	s_bcnt1_i32_b64 s22, s[28:29]
	v_cndmask_b32_e64 v6, 0, 1, s[30:31]
	v_or_b32_e32 v67, 0x500, v124
	s_add_i32 s35, s37, s22
	v_cmp_ne_u32_e64 s[26:27], 0, v6
	v_lshlrev_b32_e32 v46, 9, v67
	s_and_saveexec_b64 s[22:23], s[30:31]
	s_cbranch_execz .LBB0_832
	v_mbcnt_lo_u32_b32 v6, s26, 0
	v_mbcnt_hi_u32_b32 v6, s27, v6
	v_add_u32_e32 v6, s35, v6
	v_lshl_add_u32 v7, v6, 2, s33
	ds_write_b32 v7, v67
	v_and_b32_e32 v7, 0x7ffffe0, v6
	v_lshlrev_b32_e32 v48, 5, v6
	v_lshl_add_u32 v7, v7, 2, s33
	v_and_b32_e32 v48, 0x60, v48
	v_and_b32_e32 v6, 28, v6
	v_add3_u32 v6, v7, v48, v6
	ds_write_b32 v6, v46 offset:4096

; __device__ __forceinline__ void topk_list(const unsigned (&uk)[32], LAS int* list, LAS float* listr, LAS unsigned* listT, const GAS f32x4* sak, int lane) {
;     ...
;     int base = 0, eqseen = 0;
; #pragma unroll
;     for (int rr = 0; rr < 32; ++rr) {
;         const bool gt = uk[rr] > T, eq = uk[rr] == T;
;         const unsigned long long meq = __builtin_amdgcn_ballot_w64(eq);
;         const int erank = eqseen + (int)__builtin_amdgcn_mbcnt_hi((unsigned)(meq >> 32), __builtin_amdgcn_mbcnt_lo((unsigned)meq, 0u));
;         const bool sel = gt || (eq && erank < need_eq);
;         const unsigned long long ms = __builtin_amdgcn_ballot_w64(sel);
;         const int pos = base + (int)__builtin_amdgcn_mbcnt_hi((unsigned)(ms >> 32), __builtin_amdgcn_mbcnt_lo((unsigned)ms, 0u));
;         if (sel) { list[pos] = 64 * rr + lane; listT[((pos >> 5) * 4 + (pos & 3)) * 8 + ((pos >> 2) & 7)] = (unsigned)(64 * rr + lane) * 512u; }
;         base += __builtin_popcountll(ms); eqseen += __builtin_popcountll(meq);
;     }
.LBB0_844:
	s_or_b64 exec, exec, s[16:17]
	s_cmpk_le_u32 s81, 0x600
	s_cbranch_scc1 .LBB0_876
	s_bcnt1_i32_b64 s16, s[18:19]
	s_add_i32 s24, s26, s16
	v_cmp_eq_u32_e64 s[16:17], v175, v85
	s_mov_b64 s[22:23], -1
	s_and_saveexec_b64 s[18:19], s[14:15]
	v_mbcnt_lo_u32_b32 v6, s16, 0
	v_mbcnt_hi_u32_b32 v6, s17, v6
	v_add_u32_e32 v6, s24, v6
	v_cmp_gt_i32_e64 s[14:15], s82, v6
	s_and_b64 s[14:15], s[16:17], s[14:15]
	s_orn2_b64 s[22:23], s[14:15], exec
	s_or_b64 exec, exec, s[18:19]
	s_bcnt1_i32_b64 s14, s[20:21]
	v_cndmask_b32_e64 v6, 0, 1, s[22:23]
	v_or_b32_e32 v75, 0x600, v124
	s_add_i32 s25, s27, s14
	v_cmp_ne_u32_e64 s[18:19], 0, v6
	v_lshlrev_b32_e32 v70, 9, v75
	s_and_saveexec_b64 s[14:15], s[22:23]
	s_cbranch_execz .LBB0_848
	v_mbcnt_lo_u32_b32 v6, s18, 0
	v_mbcnt_hi_u32_b32 v6, s19, v6
	v_add_u32_e32 v6, s25, v6
	v_lshl_add_u32 v7, v6, 2, s33
	ds_write_b32 v7, v75
	v_and_b32_e32 v7, 0x3fffffe0, v6
	v_lshlrev_b32_e32 v72, 5, v6
	v_lshl_add_u32 v7, v7, 2, s33
	v_and_b32_e32 v72, 0x60, v72
	v_and_b32_e32 v6, 28, v6
	v_add3_u32 v6, v7, v72, v6
	ds_write_b32 v6, v70 offset:4096

; __device__ __forceinline__ void topk_list(const unsigned (&uk)[32], LAS int* list, LAS float* listr, LAS unsigned* listT, const GAS f32x4* sak, int lane) {
;     ...
;     int base = 0, eqseen = 0;
; #pragma unroll
;     for (int rr = 0; rr < 32; ++rr) {
;         const bool gt = uk[rr] > T, eq = uk[rr] == T;
;         const unsigned long long meq = __builtin_amdgcn_ballot_w64(eq);
;         const int erank = eqseen + (int)__builtin_amdgcn_mbcnt_hi((unsigned)(meq >> 32), __builtin_amdgcn_mbcnt_lo((unsigned)meq, 0u));
;         const bool sel = gt || (eq && erank < need_eq);
;         const unsigned long long ms = __builtin_amdgcn_ballot_w64(sel);
;         const int pos = base + (int)__builtin_amdgcn_mbcnt_hi((unsigned)(ms >> 32), __builtin_amdgcn_mbcnt_lo((unsigned)ms, 0u));
;         if (sel) { list[pos] = 64 * rr + lane; listT[((pos >> 5) * 4 + (pos & 3)) * 8 + ((pos >> 2) & 7)] = (unsigned)(64 * rr + lane) * 512u; }
;         base += __builtin_popcountll(ms); eqseen += __builtin_popcountll(meq);
;     }
.LBB0_860:
	s_or_b64 exec, exec, s[8:9]
	s_cmpk_le_u32 s81, 0x700
	s_cbranch_scc1 .LBB0_876
	s_bcnt1_i32_b64 s8, s[10:11]
	s_add_i32 s16, s18, s8
	v_cmp_eq_u32_e64 s[8:9], v100, v85
	s_mov_b64 s[14:15], -1
	s_and_saveexec_b64 s[10:11], s[4:5]
	v_mbcnt_lo_u32_b32 v6, s8, 0
	v_mbcnt_hi_u32_b32 v6, s9, v6
	v_add_u32_e32 v6, s16, v6
	v_cmp_gt_i32_e64 s[4:5], s82, v6
	s_and_b64 s[4:5], s[8:9], s[4:5]
	s_orn2_b64 s[14:15], s[4:5], exec
	s_or_b64 exec, exec, s[10:11]
	s_bcnt1_i32_b64 s4, s[12:13]
	v_cndmask_b32_e64 v6, 0, 1, s[14:15]
	v_or_b32_e32 v83, 0x700, v124
	s_add_i32 s17, s19, s4
	v_cmp_ne_u32_e64 s[10:11], 0, v6
	v_lshlrev_b32_e32 v78, 9, v83
	s_and_saveexec_b64 s[4:5], s[14:15]
	s_cbranch_execz .LBB0_864
	v_mbcnt_lo_u32_b32 v6, s10, 0
	v_mbcnt_hi_u32_b32 v6, s11, v6
	v_add_u32_e32 v6, s17, v6
	v_lshl_add_u32 v7, v6, 2, s33
	ds_write_b32 v7, v83
	v_and_b32_e32 v7, 0x3fffffe0, v6
	v_lshlrev_b32_e32 v80, 5, v6
	v_lshl_add_u32 v7, v7, 2, s33
	v_and_b32_e32 v80, 0x60, v80
	v_and_b32_e32 v6, 28, v6
	v_add3_u32 v6, v7, v80, v6
	ds_write_b32 v6, v78 offset:4096

; __device__ __forceinline__ void topk_list(const unsigned (&uk)[32], LAS int* list, LAS float* listr, LAS unsigned* listT, const GAS f32x4* sak, int lane) {
;     ...
;     int base = 0, eqseen = 0;
; #pragma unroll
;     for (int rr = 0; rr < 32; ++rr) {
;         const bool gt = uk[rr] > T, eq = uk[rr] == T;
;         const unsigned long long meq = __builtin_amdgcn_ballot_w64(eq);
;         const int erank = eqseen + (int)__builtin_amdgcn_mbcnt_hi((unsigned)(meq >> 32), __builtin_amdgcn_mbcnt_lo((unsigned)meq, 0u));
;         const bool sel = gt || (eq && erank < need_eq);
;         const unsigned long long ms = __builtin_amdgcn_ballot_w64(sel);
;         const int pos = base + (int)__builtin_amdgcn_mbcnt_hi((unsigned)(ms >> 32), __builtin_amdgcn_mbcnt_lo((unsigned)ms, 0u));
;         if (sel) { list[pos] = 64 * rr + lane; listT[((pos >> 5) * 4 + (pos & 3)) * 8 + ((pos >> 2) & 7)] = (unsigned)(64 * rr + lane) * 512u; }
;         base += __builtin_popcountll(ms); eqseen += __builtin_popcountll(meq);
;     }
.LBB0_910:
	s_or_b64 exec, exec, s[48:49]
	s_cmpk_le_u32 s81, 0x200
	s_cbranch_scc1 .LBB0_1006
	s_bcnt1_i32_b64 s48, s[50:51]
	s_add_i32 s56, s58, s48
	v_cmp_eq_u32_e64 s[48:49], v120, v4
	s_mov_b64 s[54:55], -1
	s_and_saveexec_b64 s[50:51], s[46:47]
	v_mbcnt_lo_u32_b32 v2, s48, 0
	v_mbcnt_hi_u32_b32 v2, s49, v2
	v_add_u32_e32 v2, s56, v2
	v_cmp_gt_i32_e64 s[46:47], s78, v2
	s_and_b64 s[46:47], s[48:49], s[46:47]
	s_orn2_b64 s[54:55], s[46:47], exec
	s_or_b64 exec, exec, s[50:51]
	s_bcnt1_i32_b64 s46, s[52:53]
	v_cndmask_b32_e64 v2, 0, 1, s[54:55]
	s_add_i32 s57, s59, s46
	v_cmp_ne_u32_e64 s[50:51], 0, v2
	s_and_saveexec_b64 s[46:47], s[54:55]
	s_cbranch_execz .LBB0_914
	v_mbcnt_lo_u32_b32 v2, s50, 0
	v_mbcnt_hi_u32_b32 v2, s51, v2
	v_add_u32_e32 v2, s57, v2
	v_lshl_add_u32 v3, v2, 2, s33
	ds_write_b32 v3, v22 offset:2048
	v_and_b32_e32 v3, 0x7fe0, v2
	v_lshlrev_b32_e32 v5, 5, v2
	v_lshl_add_u32 v3, v3, 2, s33
	v_and_b32_e32 v5, 0x60, v5
	v_and_b32_e32 v2, 28, v2
	v_add3_u32 v2, v3, v5, v2
	ds_write_b32 v2, v19 offset:5120

; __device__ __forceinline__ void topk_list(const unsigned (&uk)[32], LAS int* list, LAS float* listr, LAS unsigned* listT, const GAS f32x4* sak, int lane) {
;     ...
;     int base = 0, eqseen = 0;
; #pragma unroll
;     for (int rr = 0; rr < 32; ++rr) {
;         const bool gt = uk[rr] > T, eq = uk[rr] == T;
;         const unsigned long long meq = __builtin_amdgcn_ballot_w64(eq);
;         const int erank = eqseen + (int)__builtin_amdgcn_mbcnt_hi((unsigned)(meq >> 32), __builtin_amdgcn_mbcnt_lo((unsigned)meq, 0u));
;         const bool sel = gt || (eq && erank < need_eq);
;         const unsigned long long ms = __builtin_amdgcn_ballot_w64(sel);
;         const int pos = base + (int)__builtin_amdgcn_mbcnt_hi((unsigned)(ms >> 32), __builtin_amdgcn_mbcnt_lo((unsigned)ms, 0u));
;         if (sel) { list[pos] = 64 * rr + lane; listT[((pos >> 5) * 4 + (pos & 3)) * 8 + ((pos >> 2) & 7)] = (unsigned)(64 * rr + lane) * 512u; }
;         base += __builtin_popcountll(ms); eqseen += __builtin_popcountll(meq);
;     }
.LBB0_926:
	s_or_b64 exec, exec, s[40:41]
	s_cmpk_le_u32 s81, 0x300
	s_cbranch_scc1 .LBB0_1006
	s_bcnt1_i32_b64 s40, s[42:43]
	s_add_i32 s48, s50, s40
	v_cmp_eq_u32_e64 s[40:41], v135, v4
	s_mov_b64 s[46:47], -1
	s_and_saveexec_b64 s[42:43], s[38:39]
	v_mbcnt_lo_u32_b32 v2, s40, 0
	v_mbcnt_hi_u32_b32 v2, s41, v2
	v_add_u32_e32 v2, s48, v2
	v_cmp_gt_i32_e64 s[38:39], s78, v2
	s_and_b64 s[38:39], s[40:41], s[38:39]
	s_orn2_b64 s[46:47], s[38:39], exec
	s_or_b64 exec, exec, s[42:43]
	s_bcnt1_i32_b64 s38, s[44:45]
	v_cndmask_b32_e64 v2, 0, 1, s[46:47]
	s_add_i32 s49, s51, s38
	v_cmp_ne_u32_e64 s[42:43], 0, v2
	s_and_saveexec_b64 s[38:39], s[46:47]
	s_cbranch_execz .LBB0_930
	v_mbcnt_lo_u32_b32 v2, s42, 0
	v_mbcnt_hi_u32_b32 v2, s43, v2
	v_add_u32_e32 v2, s49, v2
	v_lshl_add_u32 v3, v2, 2, s33
	ds_write_b32 v3, v30 offset:2048
	v_and_b32_e32 v3, 0x7ffe0, v2
	v_lshlrev_b32_e32 v5, 5, v2
	v_lshl_add_u32 v3, v3, 2, s33
	v_and_b32_e32 v5, 0x60, v5
	v_and_b32_e32 v2, 28, v2
	v_add3_u32 v2, v3, v5, v2
	ds_write_b32 v2, v25 offset:5120

; __device__ __forceinline__ void topk_list(const unsigned (&uk)[32], LAS int* list, LAS float* listr, LAS unsigned* listT, const GAS f32x4* sak, int lane) {
;     ...
;     int base = 0, eqseen = 0;
; #pragma unroll
;     for (int rr = 0; rr < 32; ++rr) {
;         const bool gt = uk[rr] > T, eq = uk[rr] == T;
;         const unsigned long long meq = __builtin_amdgcn_ballot_w64(eq);
;         const int erank = eqseen + (int)__builtin_amdgcn_mbcnt_hi((unsigned)(meq >> 32), __builtin_amdgcn_mbcnt_lo((unsigned)meq, 0u));
;         const bool sel = gt || (eq && erank < need_eq);
;         const unsigned long long ms = __builtin_amdgcn_ballot_w64(sel);
;         const int pos = base + (int)__builtin_amdgcn_mbcnt_hi((unsigned)(ms >> 32), __builtin_amdgcn_mbcnt_lo((unsigned)ms, 0u));
;         if (sel) { list[pos] = 64 * rr + lane; listT[((pos >> 5) * 4 + (pos & 3)) * 8 + ((pos >> 2) & 7)] = (unsigned)(64 * rr + lane) * 512u; }
;         base += __builtin_popcountll(ms); eqseen += __builtin_popcountll(meq);
;     }
.LBB0_942:
	s_or_b64 exec, exec, s[30:31]
	s_cmpk_le_u32 s81, 0x400
	s_cbranch_scc1 .LBB0_1006
	s_bcnt1_i32_b64 s30, s[34:35]
	s_add_i32 s40, s42, s30
	v_cmp_eq_u32_e64 s[30:31], v139, v4
	s_mov_b64 s[38:39], -1
	s_and_saveexec_b64 s[34:35], s[28:29]
	v_mbcnt_lo_u32_b32 v2, s30, 0
	v_mbcnt_hi_u32_b32 v2, s31, v2
	v_add_u32_e32 v2, s40, v2
	v_cmp_gt_i32_e64 s[28:29], s78, v2
	s_and_b64 s[28:29], s[30:31], s[28:29]
	s_orn2_b64 s[38:39], s[28:29], exec
	s_or_b64 exec, exec, s[34:35]
	s_bcnt1_i32_b64 s28, s[36:37]
	v_cndmask_b32_e64 v2, 0, 1, s[38:39]
	s_add_i32 s41, s43, s28
	v_cmp_ne_u32_e64 s[34:35], 0, v2
	s_and_saveexec_b64 s[28:29], s[38:39]
	s_cbranch_execz .LBB0_946
	v_mbcnt_lo_u32_b32 v2, s34, 0
	v_mbcnt_hi_u32_b32 v2, s35, v2
	v_add_u32_e32 v2, s41, v2
	v_lshl_add_u32 v3, v2, 2, s33
	ds_write_b32 v3, v43 offset:2048
	v_and_b32_e32 v3, 0x7fffe0, v2
	v_lshlrev_b32_e32 v5, 5, v2
	v_lshl_add_u32 v3, v3, 2, s33
	v_and_b32_e32 v5, 0x60, v5
	v_and_b32_e32 v2, 28, v2
	v_add3_u32 v2, v3, v5, v2
	ds_write_b32 v2, v33 offset:5120

; __device__ __forceinline__ void topk_list(const unsigned (&uk)[32], LAS int* list, LAS float* listr, LAS unsigned* listT, const GAS f32x4* sak, int lane) {
;     ...
;     int base = 0, eqseen = 0;
; #pragma unroll
;     for (int rr = 0; rr < 32; ++rr) {
;         const bool gt = uk[rr] > T, eq = uk[rr] == T;
;         const unsigned long long meq = __builtin_amdgcn_ballot_w64(eq);
;         const int erank = eqseen + (int)__builtin_amdgcn_mbcnt_hi((unsigned)(meq >> 32), __builtin_amdgcn_mbcnt_lo((unsigned)meq, 0u));
;         const bool sel = gt || (eq && erank < need_eq);
;         const unsigned long long ms = __builtin_amdgcn_ballot_w64(sel);
;         const int pos = base + (int)__builtin_amdgcn_mbcnt_hi((unsigned)(ms >> 32), __builtin_amdgcn_mbcnt_lo((unsigned)ms, 0u));
;         if (sel) { list[pos] = 64 * rr + lane; listT[((pos >> 5) * 4 + (pos & 3)) * 8 + ((pos >> 2) & 7)] = (unsigned)(64 * rr + lane) * 512u; }
;         base += __builtin_popcountll(ms); eqseen += __builtin_popcountll(meq);
;     }
.LBB0_958:
	s_or_b64 exec, exec, s[22:23]
	s_cmpk_le_u32 s81, 0x500
	s_cbranch_scc1 .LBB0_1006
	s_bcnt1_i32_b64 s22, s[24:25]
	s_add_i32 s30, s34, s22
	v_cmp_eq_u32_e64 s[22:23], v151, v4
	s_mov_b64 s[28:29], -1
	s_and_saveexec_b64 s[24:25], s[20:21]
	v_mbcnt_lo_u32_b32 v2, s22, 0
	v_mbcnt_hi_u32_b32 v2, s23, v2
	v_add_u32_e32 v2, s30, v2
	v_cmp_gt_i32_e64 s[20:21], s78, v2
	s_and_b64 s[20:21], s[22:23], s[20:21]
	s_orn2_b64 s[28:29], s[20:21], exec
	s_or_b64 exec, exec, s[24:25]
	s_bcnt1_i32_b64 s20, s[26:27]
	v_cndmask_b32_e64 v2, 0, 1, s[28:29]
	s_add_i32 s31, s35, s20
	v_cmp_ne_u32_e64 s[24:25], 0, v2
	s_and_saveexec_b64 s[20:21], s[28:29]
	s_cbranch_execz .LBB0_962
	v_mbcnt_lo_u32_b32 v2, s24, 0
	v_mbcnt_hi_u32_b32 v2, s25, v2
	v_add_u32_e32 v2, s31, v2
	v_lshl_add_u32 v3, v2, 2, s33
	ds_write_b32 v3, v67 offset:2048
	v_and_b32_e32 v3, 0x7ffffe0, v2
	v_lshlrev_b32_e32 v5, 5, v2
	v_lshl_add_u32 v3, v3, 2, s33
	v_and_b32_e32 v5, 0x60, v5
	v_and_b32_e32 v2, 28, v2
	v_add3_u32 v2, v3, v5, v2
	ds_write_b32 v2, v46 offset:5120

; __device__ __forceinline__ void topk_list(const unsigned (&uk)[32], LAS int* list, LAS float* listr, LAS unsigned* listT, const GAS f32x4* sak, int lane) {
;     ...
;     int base = 0, eqseen = 0;
; #pragma unroll
;     for (int rr = 0; rr < 32; ++rr) {
;         const bool gt = uk[rr] > T, eq = uk[rr] == T;
;         const unsigned long long meq = __builtin_amdgcn_ballot_w64(eq);
;         const int erank = eqseen + (int)__builtin_amdgcn_mbcnt_hi((unsigned)(meq >> 32), __builtin_amdgcn_mbcnt_lo((unsigned)meq, 0u));
;         const bool sel = gt || (eq && erank < need_eq);
;         const unsigned long long ms = __builtin_amdgcn_ballot_w64(sel);
;         const int pos = base + (int)__builtin_amdgcn_mbcnt_hi((unsigned)(ms >> 32), __builtin_amdgcn_mbcnt_lo((unsigned)ms, 0u));
;         if (sel) { list[pos] = 64 * rr + lane; listT[((pos >> 5) * 4 + (pos & 3)) * 8 + ((pos >> 2) & 7)] = (unsigned)(64 * rr + lane) * 512u; }
;         base += __builtin_popcountll(ms); eqseen += __builtin_popcountll(meq);
;     }
.LBB0_974:
	s_or_b64 exec, exec, s[14:15]
	s_cmpk_le_u32 s81, 0x600
	s_cbranch_scc1 .LBB0_1006
	s_bcnt1_i32_b64 s14, s[16:17]
	s_add_i32 s22, s24, s14
	v_cmp_eq_u32_e64 s[14:15], v163, v4
	s_mov_b64 s[20:21], -1
	s_and_saveexec_b64 s[16:17], s[12:13]
	v_mbcnt_lo_u32_b32 v2, s14, 0
	v_mbcnt_hi_u32_b32 v2, s15, v2
	v_add_u32_e32 v2, s22, v2
	v_cmp_gt_i32_e64 s[12:13], s78, v2
	s_and_b64 s[12:13], s[14:15], s[12:13]
	s_orn2_b64 s[20:21], s[12:13], exec
	s_or_b64 exec, exec, s[16:17]
	s_bcnt1_i32_b64 s12, s[18:19]
	v_cndmask_b32_e64 v2, 0, 1, s[20:21]
	s_add_i32 s23, s25, s12
	v_cmp_ne_u32_e64 s[16:17], 0, v2
	s_and_saveexec_b64 s[12:13], s[20:21]
	s_cbranch_execz .LBB0_978
	v_mbcnt_lo_u32_b32 v2, s16, 0
	v_mbcnt_hi_u32_b32 v2, s17, v2
	v_add_u32_e32 v2, s23, v2
	v_lshl_add_u32 v3, v2, 2, s33
	ds_write_b32 v3, v75 offset:2048
	v_and_b32_e32 v3, 0x3fffffe0, v2
	v_lshlrev_b32_e32 v5, 5, v2
	v_lshl_add_u32 v3, v3, 2, s33
	v_and_b32_e32 v5, 0x60, v5
	v_and_b32_e32 v2, 28, v2
	v_add3_u32 v2, v3, v5, v2
	ds_write_b32 v2, v70 offset:5120

; __device__ __forceinline__ void topk_list(const unsigned (&uk)[32], LAS int* list, LAS float* listr, LAS unsigned* listT, const GAS f32x4* sak, int lane) {
;     ...
;     int base = 0, eqseen = 0;
; #pragma unroll
;     for (int rr = 0; rr < 32; ++rr) {
;         const bool gt = uk[rr] > T, eq = uk[rr] == T;
;         const unsigned long long meq = __builtin_amdgcn_ballot_w64(eq);
;         const int erank = eqseen + (int)__builtin_amdgcn_mbcnt_hi((unsigned)(meq >> 32), __builtin_amdgcn_mbcnt_lo((unsigned)meq, 0u));
;         const bool sel = gt || (eq && erank < need_eq);
;         const unsigned long long ms = __builtin_amdgcn_ballot_w64(sel);
;         const int pos = base + (int)__builtin_amdgcn_mbcnt_hi((unsigned)(ms >> 32), __builtin_amdgcn_mbcnt_lo((unsigned)ms, 0u));
;         if (sel) { list[pos] = 64 * rr + lane; listT[((pos >> 5) * 4 + (pos & 3)) * 8 + ((pos >> 2) & 7)] = (unsigned)(64 * rr + lane) * 512u; }
;         base += __builtin_popcountll(ms); eqseen += __builtin_popcountll(meq);
;     }
.LBB0_990:
	s_or_b64 exec, exec, s[6:7]
	s_cmpk_le_u32 s81, 0x700
	s_cbranch_scc1 .LBB0_1006
	s_bcnt1_i32_b64 s6, s[8:9]
	s_add_i32 s14, s16, s6
	v_cmp_eq_u32_e64 s[6:7], v37, v4
	s_mov_b64 s[12:13], -1
	s_and_saveexec_b64 s[8:9], s[4:5]
	v_mbcnt_lo_u32_b32 v2, s6, 0
	v_mbcnt_hi_u32_b32 v2, s7, v2
	v_add_u32_e32 v2, s14, v2
	v_cmp_gt_i32_e64 s[4:5], s78, v2
	s_and_b64 s[4:5], s[6:7], s[4:5]
	s_orn2_b64 s[12:13], s[4:5], exec
	s_or_b64 exec, exec, s[8:9]
	s_bcnt1_i32_b64 s4, s[10:11]
	v_cndmask_b32_e64 v2, 0, 1, s[12:13]
	s_add_i32 s15, s17, s4
	v_cmp_ne_u32_e64 s[8:9], 0, v2
	s_and_saveexec_b64 s[4:5], s[12:13]
	s_cbranch_execz .LBB0_994
	v_mbcnt_lo_u32_b32 v2, s8, 0
	v_mbcnt_hi_u32_b32 v2, s9, v2
	v_add_u32_e32 v2, s15, v2
	v_lshl_add_u32 v3, v2, 2, s33
	ds_write_b32 v3, v83 offset:2048
	v_and_b32_e32 v3, 0x3fffffe0, v2
	v_lshlrev_b32_e32 v5, 5, v2
	v_lshl_add_u32 v3, v3, 2, s33
	v_and_b32_e32 v5, 0x60, v5
	v_and_b32_e32 v2, 28, v2
	v_add3_u32 v2, v3, v5, v2
	ds_write_b32 v2, v78 offset:5120
